# SSD chunk loop: vmcnt(1) at loop top + DPP row-shift scan for the cumulative log-decay; cooperative-groups entry sync removed (XCD barrier census suffices)
# speedup vs baseline: 1.0137x; 1.0137x over previous
; #define LAS __attribute__((address_space(3)))
; __device__ __forceinline__ KP kparams() { KP p = (KP)__builtin_amdgcn_kernarg_segment_ptr(); asm volatile("" : "+s"(p)); return p; }
; __device__ __forceinline__ unsigned xb_add(unsigned* p, unsigned v) { return __hip_atomic_fetch_add(p, v, __ATOMIC_RELAXED, __HIP_MEMORY_SCOPE_AGENT); }
; __device__ __forceinline__ unsigned xb_xcc_id() { return (unsigned)__builtin_amdgcn_s_getreg((3 << 11) | 20) & 0xFu; }
; __device__ __forceinline__ void prologue(const Ctx& C_, LAS unsigned char* lds) {
;     ...
;     LAS float* scr = (LAS float*)(lds + C.wave * 16640);
;     const int gw = C.bid * NWAVES + C.wave, NGW = C.G * NWAVES, lane = C.lane;
;     constexpr int NB1 = NPROJ / 64;
;     constexpr int I_W1 = 16 * NB1, I_PW = 4 * 4 * 4, I_PO = 16 * 16, I_SO = 32 * 16, I_O = 16 * 16, I_UP = 16 * (DUP / 64), I_D = (DFF / 64) * 16;
;     constexpr int I_LAYER = I_W1 + I_PW + I_PO + I_SO + I_O + I_UP + I_D;
;     for (int it = gw; it < DEPTH * I_LAYER; it += NGW) {
;         const int l = it / I_LAYER; int r = it - l * I_LAYER;
;         if (r < I_W1) {
;             const int nb = r % NB1, kb = r / NB1, n0 = nb * 64, k0 = kb * 64;
;             bf16_t* dst = L_W1T + ((size_t)l * NPROJ + n0) * 1024;
;             if (n0 >= PC_DT + 64) {
;                 const int c = lane & 7;
; #pragma unroll
;                 for (int j = 0; j < 8; ++j) { const int n = (lane >> 3) + 8 * j; *(u32x4*)(dst + (size_t)n * 1024 + k0 + 8 * c) = (u32x4){0u, 0u, 0u, 0u}; }
;             } else {
;                 int sc, nv = 64;
;                 if (n0 < PC_GA) sc = n0; else if (n0 < PC_GB) sc = 6176 + (n0 - PC_GA); else if (n0 < PC_DT) sc = 7200 + (n0 - PC_GB); else { sc = 6144; nv = 32; }
;                 transpose_item(L_w_in + (size_t)l * 1024 * 8224, 8224, sc, k0, dst, 1024, L_norm1_w + l * 1024, nullptr, nv, scr, lane);
; __global__ void __launch_bounds__(NTHREADS, 2) hybrid_fwd(Params P) {
;     ...
;     {
;         const int t0 = threadIdx.x;
;         C.tid = t0; C.lane = t0 & 63; C.wave = __builtin_amdgcn_readfirstlane(t0 >> 6); C.G = gridDim.x; C.bid = blockIdx.x;
;         if (t0 < 4) ((LAS unsigned*)(lds + LDS_ST_OFF))[t0] = 0u;
;         if (t0 == 0) { KP kp0 = kparams(); (void)xb_add((unsigned*)(kp0->ws + WS_CTL) + XB_XCNT(xb_xcc_id()), 1u); }
;         __syncthreads();
;         cg::this_grid().sync();
.LBB0_5:
	s_or_b64 exec, exec, s[14:15]
	v_lshrrev_b32_e32 v2, 20, v0
	v_lshrrev_b32_e32 v0, 10, v0
	v_or_b32_e32 v0, v0, v2
	s_movk_i32 s3, 0x3ff
	v_and_or_b32 v0, v0, s3, v1
	v_cmp_eq_u32_e32 vcc, 0, v0
	s_waitcnt lgkmcnt(0)
	s_barrier
	s_barrier
	s_and_saveexec_b64 s[14:15], vcc
.LBB0_15:
	s_or_b64 exec, exec, s[14:15]
	s_lshr_b32 s36, s12, 6
	v_mbcnt_lo_u32_b32 v0, -1, 0
	v_writelane_b32 v255, s36, 0
	v_writelane_b32 v255, s38, 1
	v_mbcnt_hi_u32_b32 v174, -1, v0
	v_writelane_b32 v255, s2, 2
	v_mov_b32_e32 v72, v174
	s_mov_b32 s4, s2
	v_writelane_b32 v255, s0, 3
	s_mov_b64 s[2:3], s[0:1]
	s_barrier
	s_load_dwordx4 s[24:27], s[2:3], 0x0
	s_load_dwordx8 s[8:15], s[2:3], 0x30
	s_load_dwordx2 s[34:35], s[2:3], 0xd8
	s_load_dwordx4 s[28:31], s[2:3], 0x50
	s_lshl_b32 s5, s4, 3
	s_add_i32 s40, s5, s36
	s_lshl_b32 s42, s38, 3
	v_writelane_b32 v255, s1, 4
	s_cmpk_gt_i32 s40, 0x52ff
	s_mov_b32 s37, 0
	s_cbranch_scc1 .LBB0_182
	s_waitcnt lgkmcnt(0)
	s_add_u32 s41, s34, 0x4200000
	s_addc_u32 s43, s35, 0
	s_add_u32 s60, s34, 0x4400000
	s_addc_u32 s61, s35, 0
	s_add_u32 s62, s34, 0x4c00000
	s_addc_u32 s64, s35, 0
	s_add_u32 s65, s34, 0x5c00000
	s_addc_u32 s67, s35, 0
	s_add_u32 s63, s34, 0x6400000
	s_load_dwordx8 s[16:23], s[2:3], 0x88
	s_load_dwordx2 s[6:7], s[2:3], 0xa8
	s_load_dwordx2 s[44:45], s[2:3], 0xc0
	s_addc_u32 s66, s35, 0
	s_add_u32 s0, s34, 0x9000000
	s_mul_i32 s2, s36, 0x4100
	s_addc_u32 s71, s35, 0
	s_add_i32 s2, s2, 0
	v_lshlrev_b32_e32 v0, 2, v72
	v_lshlrev_b32_e32 v1, 3, v72
	s_waitcnt lgkmcnt(0)
	s_cmp_lg_u64 s[22:23], 0
	v_and_b32_e32 v74, 60, v0
	v_ashrrev_i32_e32 v0, 3, v72
	v_and_b32_e32 v78, 56, v1
	s_cselect_b64 s[46:47], -1, 0
	s_cmp_lg_u64 s[16:17], 0
	v_mul_u32_u24_e32 v1, 0x104, v78
	v_lshlrev_b32_e32 v2, 2, v0
	s_cselect_b64 s[48:49], -1, 0
	s_cmp_lg_u64 s[28:29], 0
	v_ashrrev_i32_e32 v76, 4, v72
	s_movk_i32 s3, 0x104
	v_add3_u32 v79, s2, v1, v2
	s_movk_i32 s5, 0x1600
	v_add_u32_e32 v2, 8, v0
	v_add_u32_e32 v4, 16, v0
	v_add_u32_e32 v6, 24, v0
	v_add_u32_e32 v8, 32, v0
	v_add_u32_e32 v10, 40, v0
	v_add_u32_e32 v12, 48, v0
	v_add_u32_e32 v14, 56, v0
	s_cselect_b64 s[50:51], -1, 0
	s_cmp_lg_u64 s[10:11], 0
	v_lshl_add_u32 v73, v74, 2, s2
	v_mul_lo_u32 v16, v76, s3
	v_mad_i64_i32 v[80:81], s[2:3], v0, s5, 0
	v_mad_i64_i32 v[82:83], s[2:3], v2, s5, 0
	v_mad_i64_i32 v[84:85], s[2:3], v4, s5, 0
	v_mad_i64_i32 v[86:87], s[2:3], v6, s5, 0
	v_mad_i64_i32 v[88:89], s[2:3], v8, s5, 0
	v_mad_i64_i32 v[120:121], s[2:3], v10, s5, 0
	v_mad_i64_i32 v[128:129], s[2:3], v12, s5, 0
	v_mad_i64_i32 v[136:137], s[2:3], v14, s5, 0
	s_cselect_b64 s[52:53], -1, 0
	s_lshl_b32 s5, s4, 7
	s_lshl_b32 s33, s36, 4
	v_writelane_b32 v255, s0, 5
	v_ashrrev_i32_e32 v1, 31, v0
	v_ashrrev_i32_e32 v3, 31, v2
	v_ashrrev_i32_e32 v5, 31, v4
	v_ashrrev_i32_e32 v7, 31, v6
	v_ashrrev_i32_e32 v9, 31, v8
	v_ashrrev_i32_e32 v11, 31, v10
	v_ashrrev_i32_e32 v13, 31, v12
	v_ashrrev_i32_e32 v15, 31, v14
	s_add_i32 s72, s5, s33
	s_lshl_b32 s5, s4, 9
	s_lshl_b32 s33, s36, 6
	s_lshl_b32 s4, s4, 5
	s_lshl_b32 s0, s36, 2
	v_add_u32_e32 v75, v73, v16
	v_add_u32_e32 v175, 0x410, v16
	v_add_u32_e32 v176, 0x820, v16
	v_add_u32_e32 v177, 0x1040, v16
	v_add_u32_e32 v178, 0x1860, v16
	v_add_u32_e32 v179, 0x2080, v16
	v_add_u32_e32 v180, 0x28a0, v16
	v_lshlrev_b64 v[90:91], 11, v[0:1]
	v_lshlrev_b64 v[92:93], 11, v[2:3]
	v_lshlrev_b64 v[94:95], 11, v[4:5]
	v_lshlrev_b64 v[96:97], 11, v[6:7]
	v_lshlrev_b64 v[98:99], 12, v[0:1]
	v_lshlrev_b64 v[100:101], 12, v[2:3]
	v_lshlrev_b64 v[102:103], 12, v[4:5]
	v_lshlrev_b64 v[104:105], 12, v[6:7]
	v_lshlrev_b64 v[106:107], 9, v[0:1]
	v_lshlrev_b64 v[108:109], 9, v[2:3]
	v_lshlrev_b64 v[110:111], 9, v[4:5]
	v_lshlrev_b64 v[112:113], 9, v[6:7]
	v_lshlrev_b64 v[114:115], 11, v[8:9]
	v_lshlrev_b64 v[116:117], 12, v[8:9]
	v_lshlrev_b64 v[118:119], 9, v[8:9]
	v_lshlrev_b64 v[122:123], 11, v[10:11]
	v_lshlrev_b64 v[124:125], 12, v[10:11]
	v_lshlrev_b64 v[126:127], 9, v[10:11]
	v_lshlrev_b64 v[130:131], 11, v[12:13]
	v_lshlrev_b64 v[132:133], 12, v[12:13]
	v_lshlrev_b64 v[134:135], 9, v[12:13]
	v_lshlrev_b64 v[138:139], 11, v[14:15]
	v_lshlrev_b64 v[140:141], 12, v[14:15]
	v_lshlrev_b64 v[142:143], 9, v[14:15]
	v_cmp_gt_u32_e64 s[2:3], 32, v74
	v_ashrrev_i32_e32 v77, 31, v76
	s_lshl_b32 s73, s38, 7
	s_add_i32 s74, s5, s33
	s_lshl_b32 s75, s38, 9
	s_add_i32 s76, s4, s0
	s_lshl_b32 s77, s38, 5
	s_movk_i32 s78, 0x5800
	s_movk_i32 s79, 0x4000
	s_mov_b32 s80, 0x8000
	s_mov_b32 s81, 0xc000
	s_mov_b32 s82, 0x10000
	s_mov_b32 s83, 0x14000
	s_mov_b32 s84, 0x18000
	s_mov_b32 s85, 0x1c000
	s_mov_b32 s86, 0x20000
	s_mov_b32 s87, 0x24000
	s_mov_b32 s88, 0x28000
	s_mov_b32 s89, 0x2c000
	s_mov_b32 s90, 0x30000
	s_mov_b32 s91, 0x34000
	s_mov_b32 s92, 0x38000
	s_mov_b32 s93, 0x3c000
	s_movk_i32 s94, 0x2000
	s_movk_i32 s95, 0x6000
	s_mov_b32 s96, 0xa000
	s_mov_b32 s97, 0xe000
	s_mov_b32 s68, 0xf000
	s_mov_b32 s69, 0x8080
	s_mov_b32 s70, s40
	v_add_u32_e32 v181, 4, v76
	v_mov_b32_e32 v1, 0
	s_branch .LBB0_18

; __device__ __forceinline__ float shup(float v, int d, int lane) { return __builtin_bit_cast(float, __builtin_amdgcn_ds_bpermute((lane - d) << 2, __builtin_bit_cast(int, v))); }
; __device__ __forceinline__ float shidx(float v, int src) { return __builtin_bit_cast(float, __builtin_amdgcn_ds_bpermute(src << 2, __builtin_bit_cast(int, v))); }
; __device__ __forceinline__ void ssd_phase(const Ctx& C_, LAS unsigned char* lds_in, int l) {
;     ...
;         const float d = dtraw;
;         float cs = d * a_h;
; #pragma unroll
;         for (int o_ = 1; o_ < 64; o_ <<= 1) { const float v_ = shup(cs, o_, lane); if (lane >= o_) cs += v_; }
;         const float clast = shidx(cs, 63);
;         if (wave == 7) scum[lane] = cs;
.LBB0_672:
	s_waitcnt vmcnt(1)
	v_mul_f32_e64 v42, v148, -v67
	s_and_b64 vcc, exec, s[44:45]
	s_nop 0
	v_add_f32_dpp v42, v42, v42 row_shr:1 row_mask:0xf bank_mask:0xf
	s_nop 1
	v_add_f32_dpp v42, v42, v42 row_shr:2 row_mask:0xf bank_mask:0xf
	s_nop 1
	v_add_f32_dpp v42, v42, v42 row_shr:4 row_mask:0xf bank_mask:0xf
	s_nop 1
	v_add_f32_dpp v42, v42, v42 row_shr:8 row_mask:0xf bank_mask:0xf
	s_nop 1
	v_add_f32_dpp v42, v42, v42 row_bcast:15 row_mask:0xa bank_mask:0xf
	s_nop 1
	v_add_f32_dpp v42, v42, v42 row_bcast:31 row_mask:0xc bank_mask:0xf
	s_nop 1
	v_readlane_b32 s67, v42, 63
	s_cbranch_vccnz .LBB0_674
	ds_write_b32 v108, v42
